# combo3 + next queue ticket prefetched at each mixer unit end (returning atomic overlaps store drain; publish ack no longer waited)
# speedup vs baseline: 1.0049x; 1.0049x over previous
; #define LAS __attribute__((address_space(3)))
; __device__ __forceinline__ int opaque_tid() { int t; asm volatile("v_mov_b32 %0, %1" : "=v"(t) : "v"((int)threadIdx.x)); return t; }
; __global__ void __launch_bounds__(NTHREADS, 2) mega_fwd(Params P) {
;     ...
;         {
;             LAS int* qslot = (LAS int*)(ldsl + RING_BYTES + 1024);
;             const int n_gqa = 384, n_na = 384, n_sg = 132, n_cx = lastl ? 0 : 24;
;             const int n_prod = n_gqa + n_na + n_sg + n_cx;
;             const int ntot = n_prod + 256 + (lastl ? 0 : 24);
;             unsigned* cw = ctl + CW_DEP + (size_t)l * 66 * 16;
;             for (;;) {
;                 if (opaque_tid() == 0) qslot[0] = (int)atomicAdd(ctl + 64 * (l + 1), 1u);
.LBB0_437:
	s_or_b64 exec, exec, s[34:35]
	v_readlane_b32 s0, v252, 11
	v_readlane_b32 s1, v252, 12
	s_and_b64 s[0:1], s[0:1], exec
	s_cselect_b32 s0, 24, 0
	s_or_b32 s1, s0, 0x384
	v_writelane_b32 v252, s1, 15
	s_lshl_b32 s0, s0, 1
	s_or_b32 s52, s0, 0x484
	s_mov_b64 s[0:1], s[76:77]
	v_readlane_b32 s20, v252, 9
	s_waitcnt lgkmcnt(0)
	s_barrier
	s_mul_i32 s3, s20, 0x1080
	s_mul_hi_u32 s2, s20, 0x1080
	s_add_u32 s0, s0, s3
	s_addc_u32 s1, s1, s2
	v_readlane_b32 s21, v252, 10
	s_add_u32 s53, s0, 0x8000
	s_addc_u32 s54, s1, 0
	s_lshl_b64 s[0:1], s[20:21], 21
	v_writelane_b32 v252, s0, 16
	s_lshl_b32 s86, s20, 8
	v_readlane_b32 s4, v253, 25
	v_writelane_b32 v252, s1, 17
	s_lshl_b64 s[0:1], s[20:21], 17
	s_lshl_b64 s[2:3], s[86:87], 2
	v_readlane_b32 s8, v253, 29
	v_readlane_b32 s9, v253, 30
	s_add_u32 s2, s8, s2
	s_addc_u32 s3, s9, s3
	v_writelane_b32 v252, s2, 18
	v_readlane_b32 s6, v253, 27
	v_readlane_b32 s7, v253, 28
	v_writelane_b32 v252, s3, 19
	v_readlane_b32 s2, v254, 10
	s_add_u32 s0, s2, s0
	v_writelane_b32 v252, s0, 20
	v_readlane_b32 s0, v254, 11
	s_addc_u32 s0, s0, s1
	v_readlane_b32 s5, v253, 26
	v_writelane_b32 v252, s0, 21
	s_lshl_b64 s[0:1], s[20:21], 11
	s_add_u32 s0, s6, s0
	v_writelane_b32 v252, s0, 22
	s_addc_u32 s0, s7, s1
	v_writelane_b32 v252, s0, 23
	v_writelane_b32 v252, s52, 24
	v_writelane_b32 v252, s53, 25
	v_readlane_b32 s10, v253, 31
	v_readlane_b32 s11, v253, 32
	v_readlane_b32 s12, v253, 33
	v_readlane_b32 s13, v253, 34
	v_readlane_b32 s14, v253, 35
	v_readlane_b32 s15, v253, 36
	v_readlane_b32 s16, v253, 37
	v_readlane_b32 s17, v253, 38
	v_readlane_b32 s18, v253, 39
	v_readlane_b32 s19, v253, 40
	v_writelane_b32 v252, s54, 26
	s_mov_b32 s101, 0
	s_branch .LBB0_441

; __device__ __forceinline__ int opaque_tid() { int t; asm volatile("v_mov_b32 %0, %1" : "=v"(t) : "v"((int)threadIdx.x)); return t; }
; __global__ void __launch_bounds__(NTHREADS, 2) mega_fwd(Params P) {
;     ...
;             for (;;) {
;                 if (opaque_tid() == 0) qslot[0] = (int)atomicAdd(ctl + 64 * (l + 1), 1u);
;                 __syncthreads();
;                 const int idx = __builtin_amdgcn_readfirstlane(qslot[0]);
;                 __syncthreads();
;                 if (idx >= ntot) break;
;                 if (idx < n_gqa) {
.LBB0_441:
	s_setprio 0
	s_nop 0
	v_cmp_eq_u32_e32 vcc, 0, v214
	s_and_saveexec_b64 s[0:1], vcc
	s_cbranch_execz .LBB0_443
	s_cmp_lg_u32 s101, 0
	s_cbranch_scc1 .Lpop_have
	s_mov_b64 s[2:3], s[76:77]
	s_lshl_b64 s[4:5], s[60:61], 2
	s_add_u32 s2, s2, s4
	s_addc_u32 s3, s3, s5
	v_mov_b64_e32 v[2:3], s[2:3]
	s_waitcnt vmcnt(0)
	flat_atomic_add v0, v[2:3], v218 offset:256 sc0
	s_waitcnt vmcnt(0)
.Lpop_have:
	v_readlane_b32 s2, v254, 42
	s_nop 1
	v_mov_b32_e32 v2, s2
	s_waitcnt lgkmcnt(0)
	ds_write_b32 v2, v0
.LBB0_443:
	s_or_b64 exec, exec, s[0:1]
	s_mov_b32 s101, 0
	v_readlane_b32 s0, v254, 42
	s_waitcnt lgkmcnt(0)
	s_barrier
	v_mov_b32_e32 v0, s0
	ds_read_b32 v0, v0
	s_mov_b64 s[0:1], -1
	s_waitcnt lgkmcnt(0)
	s_barrier
	v_readfirstlane_b32 s48, v0
	s_cmp_ge_i32 s48, s52
	s_cbranch_scc1 .LBB0_440
	s_cmpk_gt_i32 s48, 0x17f
	s_cbranch_scc0 .LBB0_874
	s_cmpk_gt_u32 s48, 0x2ff
	s_cbranch_scc0 .LBB0_580
	s_cmpk_gt_u32 s48, 0x383
	s_cbranch_scc0 .LBB0_556
	v_readlane_b32 s0, v252, 15
	s_cmp_ge_i32 s48, s0
	s_mov_b64 s[0:1], -1
	s_cbranch_scc0 .LBB0_530
	v_readlane_b32 s0, v252, 15
	s_sub_i32 s2, s48, s0
	s_cmpk_gt_i32 s2, 0xff
	s_cselect_b64 s[14:15], -1, 0
	s_cmpk_lt_i32 s2, 0x100
	s_cselect_b64 s[6:7], -1, 0
	s_mov_b64 s[0:1], -1
	s_and_b64 vcc, exec, s[14:15]
	s_cbranch_vccnz .LBB0_450
	s_bfe_i32 s0, s2, 0x10002
	s_and_b32 s0, s0, 33
	s_ashr_i32 s1, s2, 3
	s_add_i32 s12, s0, s1
	s_mov_b64 s[0:1], 0

; #define PG8_WAIT_V(n) asm volatile("s_waitcnt vmcnt(" #n ")" ::: "memory")
; #define PG8_BAR __builtin_amdgcn_s_barrier()
; template <class Epi, class Sched, bool ALIGN_EPI = false, bool SP2 = false>
; __device__ __forceinline__ void gemm_phase(LAS unsigned char* lds, const Gemm g, const Sched& S, const Epi& E) {
;     ...
;     PG8_WAIT_V(0);
;     if constexpr (!ALIGN_EPI) { if (wr == 0) PG8_BAR; }
;     PG8_BAR;
.LBB0_527:
	s_waitcnt lgkmcnt(0)
	v_cmp_eq_u32_e32 vcc, 0, v214
	s_cbranch_vccz .Lpf_skip_0
	s_mov_b64 exec, vcc
	v_mov_b64_e32 v[2:3], s[76:77]
	s_nop 0
	v_lshl_add_u64 v[2:3], s[60:61], 2, v[2:3]
	flat_atomic_add v0, v[2:3], v218 offset:256 sc0
	s_mov_b64 exec, -1
.Lpf_skip_0:
	s_mov_b32 s101, 1
	s_waitcnt vmcnt(0)
	s_cmpk_gt_u32 s3, 0xff
	s_cbranch_scc1 .LBB0_529
	s_barrier

; __device__ __forceinline__ unsigned xb_add(unsigned* p, unsigned v) { return __hip_atomic_fetch_add(p, v, __ATOMIC_RELAXED, __HIP_MEMORY_SCOPE_AGENT); }
; __device__ __forceinline__ void publish_cnt(unsigned* c) {
;     asm volatile("s_waitcnt vmcnt(0)" ::: "memory");
;     __syncthreads();
;     if (threadIdx.x == 0) (void)xb_add(c, 1u);
; }
.LBB0_552:
	s_or_b64 exec, exec, s[0:1]
	s_waitcnt lgkmcnt(0)
	v_cmp_eq_u32_e32 vcc, 0, v214
	s_cbranch_vccz .Lpf_skip_1
	s_mov_b64 exec, vcc
	v_mov_b64_e32 v[2:3], s[76:77]
	s_nop 0
	v_lshl_add_u64 v[2:3], s[60:61], 2, v[2:3]
	flat_atomic_add v0, v[2:3], v218 offset:256 sc0
	s_mov_b64 exec, -1
.Lpf_skip_1:
	s_mov_b32 s101, 1
	s_waitcnt vmcnt(0) lgkmcnt(0)
	s_barrier
	s_waitcnt vmcnt(0)
	s_waitcnt lgkmcnt(0)
	s_barrier
	s_and_saveexec_b64 s[0:1], s[62:63]
	s_xor_b64 s[0:1], exec, s[0:1]
	s_cbranch_execz .LBB0_554
	s_mul_i32 s86, s2, 0x210
	s_lshl_b64 s[2:3], s[86:87], 2
	s_add_u32 s2, s53, s2
	s_addc_u32 s3, s54, s3
	v_mov_b64_e32 v[2:3], s[2:3]
	flat_atomic_add v[2:3], v218 offset:2048

; __device__ __forceinline__ unsigned xb_add(unsigned* p, unsigned v) { return __hip_atomic_fetch_add(p, v, __ATOMIC_RELAXED, __HIP_MEMORY_SCOPE_AGENT); }
; __device__ __forceinline__ void publish_cnt(unsigned* c) {
;     asm volatile("s_waitcnt vmcnt(0)" ::: "memory");
;     __syncthreads();
;     if (threadIdx.x == 0) (void)xb_add(c, 1u);
; }
.LBB0_576:
	s_or_b64 exec, exec, s[4:5]
	s_waitcnt lgkmcnt(0)
	v_cmp_eq_u32_e32 vcc, 0, v214
	s_cbranch_vccz .Lpf_skip_2
	s_mov_b64 exec, vcc
	v_mov_b64_e32 v[2:3], s[76:77]
	s_nop 0
	v_lshl_add_u64 v[2:3], s[60:61], 2, v[2:3]
	flat_atomic_add v0, v[2:3], v218 offset:256 sc0
	s_mov_b64 exec, -1
.Lpf_skip_2:
	s_mov_b32 s101, 1
	s_waitcnt vmcnt(0) lgkmcnt(0)
	s_barrier
	s_waitcnt vmcnt(0)
	s_waitcnt lgkmcnt(0)
	s_barrier
	s_and_saveexec_b64 s[0:1], s[62:63]
	s_xor_b64 s[0:1], exec, s[0:1]
	s_cbranch_execz .LBB0_578
	s_lshl_b32 s2, s3, 3
	s_and_b32 s86, s2, 0x7ffffff0
	s_lshl_b64 s[2:3], s[86:87], 2
	s_add_u32 s2, s53, s2
	s_addc_u32 s3, s54, s3
	v_mov_b64_e32 v[2:3], s[2:3]
	flat_atomic_add v[2:3], v218

; __device__ __forceinline__ unsigned xb_add(unsigned* p, unsigned v) { return __hip_atomic_fetch_add(p, v, __ATOMIC_RELAXED, __HIP_MEMORY_SCOPE_AGENT); }
; __device__ __forceinline__ void publish_cnt(unsigned* c) {
;     asm volatile("s_waitcnt vmcnt(0)" ::: "memory");
;     __syncthreads();
;     if (threadIdx.x == 0) (void)xb_add(c, 1u);
; }
.Lpf_skip_3:
	s_mov_b32 s101, 1
	s_waitcnt vmcnt(0) lgkmcnt(0)
	s_barrier
	s_waitcnt vmcnt(0)
	s_waitcnt lgkmcnt(0)
	s_barrier
	s_and_saveexec_b64 s[0:1], s[62:63]
	s_xor_b64 s[0:1], exec, s[0:1]
	s_cbranch_execz .LBB0_872
	v_readlane_b32 s2, v252, 28
	v_readlane_b32 s3, v252, 29
	s_and_b64 s[2:3], s[2:3], exec
	s_cselect_b32 s2, 33, 0
	v_readlane_b32 s3, v252, 27
	s_add_i32 s2, s2, s3
	s_lshl_b32 s2, s2, 6
	s_add_u32 s2, s53, s2
	s_addc_u32 s3, s54, 0
	v_mov_b64_e32 v[2:3], s[2:3]
	flat_atomic_add v[2:3], v218

; __device__ __forceinline__ unsigned xb_add(unsigned* p, unsigned v) { return __hip_atomic_fetch_add(p, v, __ATOMIC_RELAXED, __HIP_MEMORY_SCOPE_AGENT); }
; __device__ __forceinline__ void publish_cnt(unsigned* c) {
;     asm volatile("s_waitcnt vmcnt(0)" ::: "memory");
;     __syncthreads();
;     if (threadIdx.x == 0) (void)xb_add(c, 1u);
; }
.Lpf_skip_4:
	s_mov_b32 s101, 1
	s_waitcnt vmcnt(0) lgkmcnt(0)
	s_barrier
	s_waitcnt vmcnt(0)
	s_waitcnt lgkmcnt(0)
	s_barrier
	s_and_saveexec_b64 s[0:1], s[62:63]
	s_xor_b64 s[0:1], exec, s[0:1]
	s_cbranch_execz .LBB0_438
	s_mul_i32 s2, s18, 33
	s_add_i32 s2, s2, s3
	s_lshl_b32 s2, s2, 4
	s_ashr_i32 s3, s2, 31
	s_lshl_b64 s[2:3], s[2:3], 2
	s_add_u32 s2, s53, s2
	s_addc_u32 s3, s54, s3
	v_mov_b64_e32 v[2:3], s[2:3]
	flat_atomic_add v[2:3], v218
	s_branch .LBB0_438
